# MLA attention section rewritten with 16x16x32 bf16 MFMA (restaged K/V LDS images), simple schedule
# speedup vs baseline: 1.0492x; 1.0210x over previous
.LBB0_479:
.Lmla_begin:
	v_lshrrev_b32_e32 v217, 4, v204
	v_and_b32_e32 v218, 15, v204
	v_bfe_u32 v219, v204, 1, 3
	v_xor_b32_e32 v220, v217, v219
	v_mul_u32_u24_e32 v202, 0x180, v218
	v_lshl_add_u32 v202, v220, 4, v202
	v_xor_b32_e32 v203, 64, v202
	v_bfe_u32 v221, v204, 2, 2
	v_and_b32_e32 v222, 1, v204
	v_bfe_u32 v223, v204, 1, 1
	v_and_b32_e32 v224, 1, v217
	v_lshlrev_b32_e32 v225, 11, v217
	v_lshl_add_u32 v225, v221, 6, v225
	v_lshl_add_u32 v225, v222, 3, v225
	v_xor_b32_e32 v226, 0, v224
	v_xor_b32_e32 v227, 0, v223
	v_lshl_add_u32 v206, v226, 5, v225
	v_lshl_add_u32 v206, v227, 4, v206
	v_add_u32_e32 v250, 0x4000, v206
	v_xor_b32_e32 v226, 0, v224
	v_xor_b32_e32 v227, 1, v223
	v_lshl_add_u32 v207, v226, 5, v225
	v_lshl_add_u32 v207, v227, 4, v207
	v_add_u32_e32 v251, 0x4000, v207
	v_xor_b32_e32 v226, 1, v224
	v_xor_b32_e32 v227, 0, v223
	v_lshl_add_u32 v208, v226, 5, v225
	v_lshl_add_u32 v208, v227, 4, v208
	v_add_u32_e32 v252, 0x4000, v208
	v_xor_b32_e32 v226, 1, v224
	v_xor_b32_e32 v227, 1, v223
	v_lshl_add_u32 v209, v226, 5, v225
	v_lshl_add_u32 v209, v227, 4, v209
	v_add_u32_e32 v253, 0x4000, v209
	s_add_i32 s0, s33, 0
	s_lshl_b32 s0, s0, 6
	v_add_u32_e32 v228, s0, v204
	v_mul_u32_u24_e32 v229, 0xaab, v228
	v_lshrrev_b32_e32 v229, 16, v229
	v_mul_u32_u24_e32 v230, 24, v229
	v_sub_u32_e32 v230, v228, v230
	v_bfe_u32 v231, v229, 1, 3
	v_xor_b32_e32 v230, v230, v231
	v_lshrrev_b32_e32 v232, 5, v229
	v_lshlrev_b32_e32 v232, 5, v232
	v_bfe_u32 v233, v229, 2, 2
	v_lshl_add_u32 v232, v233, 3, v232
	v_bfe_u32 v233, v229, 4, 1
	v_lshl_add_u32 v232, v233, 2, v232
	v_and_b32_e32 v233, 3, v229
	v_add_u32_e32 v232, v232, v233
	v_mul_u32_u24_e32 v210, 0xc00, v232
	v_lshl_add_u32 v210, v230, 4, v210
	s_add_i32 s0, s33, 8
	s_lshl_b32 s0, s0, 6
	v_add_u32_e32 v228, s0, v204
	v_mul_u32_u24_e32 v229, 0xaab, v228
	v_lshrrev_b32_e32 v229, 16, v229
	v_mul_u32_u24_e32 v230, 24, v229
	v_sub_u32_e32 v230, v228, v230
	v_bfe_u32 v231, v229, 1, 3
	v_xor_b32_e32 v230, v230, v231
	v_lshrrev_b32_e32 v232, 5, v229
	v_lshlrev_b32_e32 v232, 5, v232
	v_bfe_u32 v233, v229, 2, 2
	v_lshl_add_u32 v232, v233, 3, v232
	v_bfe_u32 v233, v229, 4, 1
	v_lshl_add_u32 v232, v233, 2, v232
	v_and_b32_e32 v233, 3, v229
	v_add_u32_e32 v232, v232, v233
	v_mul_u32_u24_e32 v211, 0xc00, v232
	v_lshl_add_u32 v211, v230, 4, v211
	s_add_i32 s0, s33, 16
	s_lshl_b32 s0, s0, 6
	v_add_u32_e32 v228, s0, v204
	v_mul_u32_u24_e32 v229, 0xaab, v228
	v_lshrrev_b32_e32 v229, 16, v229
	v_mul_u32_u24_e32 v230, 24, v229
	v_sub_u32_e32 v230, v228, v230
	v_bfe_u32 v231, v229, 1, 3
	v_xor_b32_e32 v230, v230, v231
	v_lshrrev_b32_e32 v232, 5, v229
	v_lshlrev_b32_e32 v232, 5, v232
	v_bfe_u32 v233, v229, 2, 2
	v_lshl_add_u32 v232, v233, 3, v232
	v_bfe_u32 v233, v229, 4, 1
	v_lshl_add_u32 v232, v233, 2, v232
	v_and_b32_e32 v233, 3, v229
	v_add_u32_e32 v232, v232, v233
	v_mul_u32_u24_e32 v212, 0xc00, v232
	v_lshl_add_u32 v212, v230, 4, v212
	s_add_i32 s0, s33, 0
	s_lshl_b32 s0, s0, 10
	v_lshl_add_u32 v228, v204, 4, s0
	v_lshrrev_b32_e32 v229, 11, v228
	v_bfe_u32 v230, v228, 6, 3
	v_lshl_add_u32 v229, v229, 3, v230
	v_bfe_u32 v230, v228, 4, 2
	v_bfe_u32 v231, v229, 2, 2
	v_xor_b32_e32 v230, v230, v231
	v_bfe_u32 v231, v228, 9, 2
	v_lshl_add_u32 v230, v231, 2, v230
	v_lshlrev_b32_e32 v213, 11, v229
	v_lshl_add_u32 v213, v230, 4, v213
	s_add_i32 s0, s33, 8
	s_lshl_b32 s0, s0, 10
	v_lshl_add_u32 v228, v204, 4, s0
	v_lshrrev_b32_e32 v229, 11, v228
	v_bfe_u32 v230, v228, 6, 3
	v_lshl_add_u32 v229, v229, 3, v230
	v_bfe_u32 v230, v228, 4, 2
	v_bfe_u32 v231, v229, 2, 2
	v_xor_b32_e32 v230, v230, v231
	v_bfe_u32 v231, v228, 9, 2
	v_lshl_add_u32 v230, v231, 2, v230
	v_lshlrev_b32_e32 v214, 11, v229
	v_lshl_add_u32 v214, v230, 4, v214
	v_mul_u32_u24_e32 v215, 0xc00, v218
	v_lshl_add_u32 v215, v217, 4, v215
	v_add_u32_e32 v216, 0xc000, v215
	s_lshl_b32 s0, s33, 10
	s_add_i32 s46, s0, 0
	s_add_i32 s47, s0, 8192
	s_add_i32 s48, s0, 16384
	s_add_i32 s52, s0, 49152
	s_add_i32 s53, s0, 57344
	s_add_i32 s49, s0, 24576
	s_add_i32 s50, s0, 32768
	s_add_i32 s51, s0, 40960
	s_add_i32 s54, s0, 65536
	s_add_i32 s55, s0, 73728
	s_brev_b32 s6, -2
	s_mov_b32 s7, 0x20000
	s_mov_b32 s10, s6
	s_mov_b32 s11, s7
	s_lshl_b32 s0, s33, 9
	s_add_i32 s0, s0, 81920
	v_lshl_add_u32 v245, v204, 2, s0
	v_lshl_add_u32 v246, v218, 2, s0
	v_lshl_add_u32 v247, v217, 4, s0
	v_lshlrev_b32_e32 v248, 14, v217
	v_lshl_add_u32 v248, v218, 1, v248
	v_mov_b32_e32 v249, 0
	s_mov_b32 s76, s2
	s_cmpk_gt_i32 s76, 0x1ff
	s_cbranch_scc1 .Lmla_done
.Lmla_unit:
	s_and_b32 s77, s76, 7
	s_lshr_b32 s78, s76, 3
	s_lshl_b32 s78, s78, 8
	s_lshl_b32 s0, s77, 4
	v_mov_b32_e32 v217, s0
	global_load_dwordx4 v[218:221], v217, s[28:29] offset:384
	global_load_dwordx2 v[222:223], v249, s[28:29] offset:640
	s_add_i32 s0, s78, 0
	s_lshl_b32 s1, s33, 5
	s_add_i32 s0, s0, s1
	s_mul_i32 s1, s0, 0xc00
	s_mul_i32 s3, s77, 0x180
	s_add_u32 s1, s1, s3
	s_add_u32 s16, s28, 404750336
	s_addc_u32 s17, s29, 0
	s_add_u32 s16, s16, s1
	s_addc_u32 s17, s17, 0
	s_lshl_b32 s1, s0, 12
	s_lshl_b32 s3, s77, 8
	s_add_u32 s1, s1, s3
	s_add_u32 s1, s1, 0x800
	s_add_u32 s18, s28, 102760448
	s_addc_u32 s19, s29, 0
	s_add_u32 s18, s18, s1
	s_addc_u32 s19, s19, 0
	s_mul_i32 s1, s77, 0x180
	s_add_u32 s4, s28, 455081984
	s_addc_u32 s5, s29, 0
	s_add_u32 s4, s4, s1
	s_addc_u32 s5, s5, 0
	s_and_b32 s5, s5, 0xffff
	s_lshl_b32 s1, s77, 8
	s_add_u32 s8, s28, 262144000
	s_addc_u32 s9, s29, 0
	s_add_u32 s8, s8, s1
	s_addc_u32 s9, s9, 0
	s_and_b32 s9, s9, 0xffff
	s_mov_b32 s12, 0
	s_mov_b32 s13, 0
	s_mov_b32 m0, s46
	s_nop 0
	buffer_load_dwordx4 v210, s[4:7], s12 offen lds
	s_mov_b32 m0, s47
	s_nop 0
	buffer_load_dwordx4 v211, s[4:7], s12 offen lds
	s_mov_b32 m0, s48
	s_nop 0
	buffer_load_dwordx4 v212, s[4:7], s12 offen lds
	s_mov_b32 m0, s52
	s_nop 0
	buffer_load_dwordx4 v213, s[8:11], s13 offen lds
	s_mov_b32 m0, s53
	s_nop 0
	buffer_load_dwordx4 v214, s[8:11], s13 offen lds
	s_add_i32 s12, s12, 0x30000
	s_add_i32 s13, s13, 0x20000
	global_load_dwordx4 v[112:115], v215, s[16:17] offset:0
	global_load_dwordx4 v[116:119], v215, s[16:17] offset:64
	global_load_dwordx4 v[120:123], v215, s[16:17] offset:128
	global_load_dwordx4 v[124:127], v215, s[16:17] offset:192
	global_load_dwordx4 v[128:131], v215, s[16:17] offset:256
	global_load_dwordx4 v[132:135], v215, s[16:17] offset:320
	global_load_dwordx4 v[136:139], v216, s[16:17] offset:0
	global_load_dwordx4 v[140:143], v216, s[16:17] offset:64
	global_load_dwordx4 v[144:147], v216, s[16:17] offset:128
	global_load_dwordx4 v[148:151], v216, s[16:17] offset:192
	global_load_dwordx4 v[152:155], v216, s[16:17] offset:256
	global_load_dwordx4 v[156:159], v216, s[16:17] offset:320
	v_mov_b32_e32 v0, 0
	v_mov_b32_e32 v1, 0
	v_mov_b32_e32 v2, 0
	v_mov_b32_e32 v3, 0
	v_mov_b32_e32 v4, 0
	v_mov_b32_e32 v5, 0
	v_mov_b32_e32 v6, 0
	v_mov_b32_e32 v7, 0
	v_mov_b32_e32 v8, 0
	v_mov_b32_e32 v9, 0
	v_mov_b32_e32 v10, 0
	v_mov_b32_e32 v11, 0
	v_mov_b32_e32 v12, 0
	v_mov_b32_e32 v13, 0
	v_mov_b32_e32 v14, 0
	v_mov_b32_e32 v15, 0
	v_mov_b32_e32 v16, 0
	v_mov_b32_e32 v17, 0
	v_mov_b32_e32 v18, 0
	v_mov_b32_e32 v19, 0
	v_mov_b32_e32 v20, 0
	v_mov_b32_e32 v21, 0
	v_mov_b32_e32 v22, 0
	v_mov_b32_e32 v23, 0
	v_mov_b32_e32 v24, 0
	v_mov_b32_e32 v25, 0
	v_mov_b32_e32 v26, 0
	v_mov_b32_e32 v27, 0
	v_mov_b32_e32 v28, 0
	v_mov_b32_e32 v29, 0
	v_mov_b32_e32 v30, 0
	v_mov_b32_e32 v31, 0
	v_mov_b32_e32 v32, 0
	v_mov_b32_e32 v33, 0
	v_mov_b32_e32 v34, 0
	v_mov_b32_e32 v35, 0
	v_mov_b32_e32 v36, 0
	v_mov_b32_e32 v37, 0
	v_mov_b32_e32 v38, 0
	v_mov_b32_e32 v39, 0
	v_mov_b32_e32 v40, 0
	v_mov_b32_e32 v41, 0
	v_mov_b32_e32 v42, 0
	v_mov_b32_e32 v43, 0
	v_mov_b32_e32 v44, 0
	v_mov_b32_e32 v45, 0
	v_mov_b32_e32 v46, 0
	v_mov_b32_e32 v47, 0
	v_mov_b32_e32 v48, 0
	v_mov_b32_e32 v49, 0
	v_mov_b32_e32 v50, 0
	v_mov_b32_e32 v51, 0
	v_mov_b32_e32 v52, 0
	v_mov_b32_e32 v53, 0
	v_mov_b32_e32 v54, 0
	v_mov_b32_e32 v55, 0
	v_mov_b32_e32 v56, 0
	v_mov_b32_e32 v57, 0
	v_mov_b32_e32 v58, 0
	v_mov_b32_e32 v59, 0
	v_mov_b32_e32 v60, 0
	v_mov_b32_e32 v61, 0
	v_mov_b32_e32 v62, 0
	v_mov_b32_e32 v63, 0
	v_mov_b32_e32 v200, 0
	v_mov_b32_e32 v201, 0
	s_waitcnt vmcnt(0)
	v_add_f32_e32 v218, v218, v219
	v_add_f32_e32 v220, v220, v221
	v_add_f32_e32 v222, v222, v223
	v_add_f32_e32 v218, v218, v220
	v_add_f32_e32 v218, v218, v222
	v_sqrt_f32_e32 v218, v218
	s_nop 0
	v_readfirstlane_b32 s60, v218
	v_mov_b32_e32 v224, 0
	v_lshlrev_b32_e32 v226, 16, v112
	v_and_b32_e32 v227, 0xffff0000, v112
	v_fmac_f32_e32 v224, v226, v226
	v_fmac_f32_e32 v224, v227, v227
	v_lshlrev_b32_e32 v226, 16, v113
	v_and_b32_e32 v227, 0xffff0000, v113
	v_fmac_f32_e32 v224, v226, v226
	v_fmac_f32_e32 v224, v227, v227
	v_lshlrev_b32_e32 v226, 16, v114
	v_and_b32_e32 v227, 0xffff0000, v114
	v_fmac_f32_e32 v224, v226, v226
	v_fmac_f32_e32 v224, v227, v227
	v_lshlrev_b32_e32 v226, 16, v115
	v_and_b32_e32 v227, 0xffff0000, v115
	v_fmac_f32_e32 v224, v226, v226
	v_fmac_f32_e32 v224, v227, v227
	v_lshlrev_b32_e32 v226, 16, v116
	v_and_b32_e32 v227, 0xffff0000, v116
	v_fmac_f32_e32 v224, v226, v226
	v_fmac_f32_e32 v224, v227, v227
	v_lshlrev_b32_e32 v226, 16, v117
	v_and_b32_e32 v227, 0xffff0000, v117
	v_fmac_f32_e32 v224, v226, v226
	v_fmac_f32_e32 v224, v227, v227
	v_lshlrev_b32_e32 v226, 16, v118
	v_and_b32_e32 v227, 0xffff0000, v118
	v_fmac_f32_e32 v224, v226, v226
	v_fmac_f32_e32 v224, v227, v227
	v_lshlrev_b32_e32 v226, 16, v119
	v_and_b32_e32 v227, 0xffff0000, v119
	v_fmac_f32_e32 v224, v226, v226
	v_fmac_f32_e32 v224, v227, v227
	v_lshlrev_b32_e32 v226, 16, v120
	v_and_b32_e32 v227, 0xffff0000, v120
	v_fmac_f32_e32 v224, v226, v226
	v_fmac_f32_e32 v224, v227, v227
	v_lshlrev_b32_e32 v226, 16, v121
	v_and_b32_e32 v227, 0xffff0000, v121
	v_fmac_f32_e32 v224, v226, v226
	v_fmac_f32_e32 v224, v227, v227
	v_lshlrev_b32_e32 v226, 16, v122
	v_and_b32_e32 v227, 0xffff0000, v122
	v_fmac_f32_e32 v224, v226, v226
	v_fmac_f32_e32 v224, v227, v227
	v_lshlrev_b32_e32 v226, 16, v123
	v_and_b32_e32 v227, 0xffff0000, v123
	v_fmac_f32_e32 v224, v226, v226
	v_fmac_f32_e32 v224, v227, v227
	v_lshlrev_b32_e32 v226, 16, v124
	v_and_b32_e32 v227, 0xffff0000, v124
	v_fmac_f32_e32 v224, v226, v226
	v_fmac_f32_e32 v224, v227, v227
	v_lshlrev_b32_e32 v226, 16, v125
	v_and_b32_e32 v227, 0xffff0000, v125
	v_fmac_f32_e32 v224, v226, v226
	v_fmac_f32_e32 v224, v227, v227
	v_lshlrev_b32_e32 v226, 16, v126
	v_and_b32_e32 v227, 0xffff0000, v126
	v_fmac_f32_e32 v224, v226, v226
	v_fmac_f32_e32 v224, v227, v227
	v_lshlrev_b32_e32 v226, 16, v127
	v_and_b32_e32 v227, 0xffff0000, v127
	v_fmac_f32_e32 v224, v226, v226
	v_fmac_f32_e32 v224, v227, v227
	v_lshlrev_b32_e32 v226, 16, v128
	v_and_b32_e32 v227, 0xffff0000, v128
	v_fmac_f32_e32 v224, v226, v226
	v_fmac_f32_e32 v224, v227, v227
	v_lshlrev_b32_e32 v226, 16, v129
	v_and_b32_e32 v227, 0xffff0000, v129
	v_fmac_f32_e32 v224, v226, v226
	v_fmac_f32_e32 v224, v227, v227
	v_lshlrev_b32_e32 v226, 16, v130
	v_and_b32_e32 v227, 0xffff0000, v130
	v_fmac_f32_e32 v224, v226, v226
	v_fmac_f32_e32 v224, v227, v227
	v_lshlrev_b32_e32 v226, 16, v131
	v_and_b32_e32 v227, 0xffff0000, v131
	v_fmac_f32_e32 v224, v226, v226
	v_fmac_f32_e32 v224, v227, v227
	v_lshlrev_b32_e32 v226, 16, v132
	v_and_b32_e32 v227, 0xffff0000, v132
	v_fmac_f32_e32 v224, v226, v226
	v_fmac_f32_e32 v224, v227, v227
	v_lshlrev_b32_e32 v226, 16, v133
	v_and_b32_e32 v227, 0xffff0000, v133
	v_fmac_f32_e32 v224, v226, v226
	v_fmac_f32_e32 v224, v227, v227
	v_lshlrev_b32_e32 v226, 16, v134
	v_and_b32_e32 v227, 0xffff0000, v134
	v_fmac_f32_e32 v224, v226, v226
	v_fmac_f32_e32 v224, v227, v227
	v_lshlrev_b32_e32 v226, 16, v135
	v_and_b32_e32 v227, 0xffff0000, v135
	v_fmac_f32_e32 v224, v226, v226
	v_fmac_f32_e32 v224, v227, v227
	ds_write_b32 v245, v224 offset:0
	v_mov_b32_e32 v225, 0
	v_lshlrev_b32_e32 v226, 16, v136
	v_and_b32_e32 v227, 0xffff0000, v136
	v_fmac_f32_e32 v225, v226, v226
	v_fmac_f32_e32 v225, v227, v227
	v_lshlrev_b32_e32 v226, 16, v137
	v_and_b32_e32 v227, 0xffff0000, v137
	v_fmac_f32_e32 v225, v226, v226
	v_fmac_f32_e32 v225, v227, v227
	v_lshlrev_b32_e32 v226, 16, v138
	v_and_b32_e32 v227, 0xffff0000, v138
	v_fmac_f32_e32 v225, v226, v226
	v_fmac_f32_e32 v225, v227, v227
	v_lshlrev_b32_e32 v226, 16, v139
	v_and_b32_e32 v227, 0xffff0000, v139
	v_fmac_f32_e32 v225, v226, v226
	v_fmac_f32_e32 v225, v227, v227
	v_lshlrev_b32_e32 v226, 16, v140
	v_and_b32_e32 v227, 0xffff0000, v140
	v_fmac_f32_e32 v225, v226, v226
	v_fmac_f32_e32 v225, v227, v227
	v_lshlrev_b32_e32 v226, 16, v141
	v_and_b32_e32 v227, 0xffff0000, v141
	v_fmac_f32_e32 v225, v226, v226
	v_fmac_f32_e32 v225, v227, v227
	v_lshlrev_b32_e32 v226, 16, v142
	v_and_b32_e32 v227, 0xffff0000, v142
	v_fmac_f32_e32 v225, v226, v226
	v_fmac_f32_e32 v225, v227, v227
	v_lshlrev_b32_e32 v226, 16, v143
	v_and_b32_e32 v227, 0xffff0000, v143
	v_fmac_f32_e32 v225, v226, v226
	v_fmac_f32_e32 v225, v227, v227
	v_lshlrev_b32_e32 v226, 16, v144
	v_and_b32_e32 v227, 0xffff0000, v144
	v_fmac_f32_e32 v225, v226, v226
	v_fmac_f32_e32 v225, v227, v227
	v_lshlrev_b32_e32 v226, 16, v145
	v_and_b32_e32 v227, 0xffff0000, v145
	v_fmac_f32_e32 v225, v226, v226
	v_fmac_f32_e32 v225, v227, v227
	v_lshlrev_b32_e32 v226, 16, v146
	v_and_b32_e32 v227, 0xffff0000, v146
	v_fmac_f32_e32 v225, v226, v226
	v_fmac_f32_e32 v225, v227, v227
	v_lshlrev_b32_e32 v226, 16, v147
	v_and_b32_e32 v227, 0xffff0000, v147
	v_fmac_f32_e32 v225, v226, v226
	v_fmac_f32_e32 v225, v227, v227
	v_lshlrev_b32_e32 v226, 16, v148
	v_and_b32_e32 v227, 0xffff0000, v148
	v_fmac_f32_e32 v225, v226, v226
	v_fmac_f32_e32 v225, v227, v227
	v_lshlrev_b32_e32 v226, 16, v149
	v_and_b32_e32 v227, 0xffff0000, v149
	v_fmac_f32_e32 v225, v226, v226
	v_fmac_f32_e32 v225, v227, v227
	v_lshlrev_b32_e32 v226, 16, v150
	v_and_b32_e32 v227, 0xffff0000, v150
	v_fmac_f32_e32 v225, v226, v226
	v_fmac_f32_e32 v225, v227, v227
	v_lshlrev_b32_e32 v226, 16, v151
	v_and_b32_e32 v227, 0xffff0000, v151
	v_fmac_f32_e32 v225, v226, v226
	v_fmac_f32_e32 v225, v227, v227
	v_lshlrev_b32_e32 v226, 16, v152
	v_and_b32_e32 v227, 0xffff0000, v152
	v_fmac_f32_e32 v225, v226, v226
	v_fmac_f32_e32 v225, v227, v227
	v_lshlrev_b32_e32 v226, 16, v153
	v_and_b32_e32 v227, 0xffff0000, v153
	v_fmac_f32_e32 v225, v226, v226
	v_fmac_f32_e32 v225, v227, v227
	v_lshlrev_b32_e32 v226, 16, v154
	v_and_b32_e32 v227, 0xffff0000, v154
	v_fmac_f32_e32 v225, v226, v226
	v_fmac_f32_e32 v225, v227, v227
	v_lshlrev_b32_e32 v226, 16, v155
	v_and_b32_e32 v227, 0xffff0000, v155
	v_fmac_f32_e32 v225, v226, v226
	v_fmac_f32_e32 v225, v227, v227
	v_lshlrev_b32_e32 v226, 16, v156
	v_and_b32_e32 v227, 0xffff0000, v156
	v_fmac_f32_e32 v225, v226, v226
	v_fmac_f32_e32 v225, v227, v227
	v_lshlrev_b32_e32 v226, 16, v157
	v_and_b32_e32 v227, 0xffff0000, v157
	v_fmac_f32_e32 v225, v226, v226
	v_fmac_f32_e32 v225, v227, v227
	v_lshlrev_b32_e32 v226, 16, v158
	v_and_b32_e32 v227, 0xffff0000, v158
	v_fmac_f32_e32 v225, v226, v226
	v_fmac_f32_e32 v225, v227, v227
	v_lshlrev_b32_e32 v226, 16, v159
	v_and_b32_e32 v227, 0xffff0000, v159
	v_fmac_f32_e32 v225, v226, v226
	v_fmac_f32_e32 v225, v227, v227
	ds_write_b32 v245, v225 offset:256
	s_waitcnt lgkmcnt(0)
	ds_read_b32 v228, v246 offset:0
	ds_read_b32 v229, v246 offset:64
	ds_read_b32 v230, v246 offset:128
	ds_read_b32 v231, v246 offset:192
	s_waitcnt lgkmcnt(2)
	v_add_f32_e32 v228, v228, v229
	s_waitcnt lgkmcnt(0)
	v_add_f32_e32 v230, v230, v231
	v_add_f32_e32 v228, v228, v230
	v_sqrt_f32_e32 v228, v228
	s_nop 0
	v_mul_f32_e32 v160, s60, v228
	v_sub_f32_e32 v160, 0, v160
	v_mov_b32_e32 v161, v160
	v_mov_b32_e32 v162, v160
	v_mov_b32_e32 v163, v160
	ds_read_b32 v228, v246 offset:256
	ds_read_b32 v229, v246 offset:320
	ds_read_b32 v230, v246 offset:384
	ds_read_b32 v231, v246 offset:448
	s_waitcnt lgkmcnt(2)
	v_add_f32_e32 v228, v228, v229
	s_waitcnt lgkmcnt(0)
	v_add_f32_e32 v230, v230, v231
	v_add_f32_e32 v228, v228, v230
	v_sqrt_f32_e32 v228, v228
	s_nop 0
	v_mul_f32_e32 v164, s60, v228
	v_sub_f32_e32 v164, 0, v164
	v_mov_b32_e32 v165, v164
	v_mov_b32_e32 v166, v164
	v_mov_b32_e32 v167, v164
	s_waitcnt vmcnt(0) lgkmcnt(0)
	s_barrier
	s_mov_b32 s14, 0
.Lmla_tiles:
	s_mov_b32 m0, s49
	s_nop 0
	buffer_load_dwordx4 v210, s[4:7], s12 offen lds
	s_mov_b32 m0, s50
	s_nop 0
	buffer_load_dwordx4 v211, s[4:7], s12 offen lds
	s_mov_b32 m0, s51
	s_nop 0
	buffer_load_dwordx4 v212, s[4:7], s12 offen lds
	s_mov_b32 m0, s54
	s_nop 0
	buffer_load_dwordx4 v213, s[8:11], s13 offen lds
	s_mov_b32 m0, s55
	s_nop 0
	buffer_load_dwordx4 v214, s[8:11], s13 offen lds
	s_add_i32 s12, s12, 0x30000
	s_add_i32 s13, s13, 0x20000
	ds_read_b128 v[168:171], v202 offset:0
	ds_read_b128 v[172:175], v203 offset:0
	ds_read_b128 v[176:179], v202 offset:128
	ds_read_b128 v[180:183], v203 offset:128
	s_waitcnt lgkmcnt(3)
	v_mfma_f32_16x16x32_bf16 v[64:67], v[168:171], v[112:115], v[160:163]
	v_mfma_f32_16x16x32_bf16 v[68:71], v[168:171], v[136:139], v[164:167]
	ds_read_b128 v[168:171], v202 offset:256
	s_waitcnt lgkmcnt(3)
	v_mfma_f32_16x16x32_bf16 v[64:67], v[172:175], v[116:119], v[64:67]
	v_mfma_f32_16x16x32_bf16 v[68:71], v[172:175], v[140:143], v[68:71]
	ds_read_b128 v[172:175], v203 offset:256
	s_waitcnt lgkmcnt(3)
	v_mfma_f32_16x16x32_bf16 v[64:67], v[176:179], v[120:123], v[64:67]
	v_mfma_f32_16x16x32_bf16 v[68:71], v[176:179], v[144:147], v[68:71]
	ds_read_b128 v[176:179], v202 offset:6144
	s_waitcnt lgkmcnt(3)
	v_mfma_f32_16x16x32_bf16 v[64:67], v[180:183], v[124:127], v[64:67]
	v_mfma_f32_16x16x32_bf16 v[68:71], v[180:183], v[148:151], v[68:71]
	ds_read_b128 v[180:183], v203 offset:6144
	s_waitcnt lgkmcnt(3)
	v_mfma_f32_16x16x32_bf16 v[64:67], v[168:171], v[128:131], v[64:67]
	v_mfma_f32_16x16x32_bf16 v[68:71], v[168:171], v[152:155], v[68:71]
	ds_read_b128 v[168:171], v202 offset:6272
	s_waitcnt lgkmcnt(3)
	v_mfma_f32_16x16x32_bf16 v[64:67], v[172:175], v[132:135], v[64:67]
	v_mfma_f32_16x16x32_bf16 v[68:71], v[172:175], v[156:159], v[68:71]
	ds_read_b128 v[172:175], v203 offset:6272
	s_waitcnt lgkmcnt(3)
	v_mfma_f32_16x16x32_bf16 v[72:75], v[176:179], v[112:115], v[160:163]
	v_mfma_f32_16x16x32_bf16 v[76:79], v[176:179], v[136:139], v[164:167]
	ds_read_b128 v[176:179], v202 offset:6400
	s_waitcnt lgkmcnt(3)
	v_mfma_f32_16x16x32_bf16 v[72:75], v[180:183], v[116:119], v[72:75]
	v_mfma_f32_16x16x32_bf16 v[76:79], v[180:183], v[140:143], v[76:79]
	ds_read_b128 v[180:183], v203 offset:6400
	s_waitcnt lgkmcnt(3)
	v_mfma_f32_16x16x32_bf16 v[72:75], v[168:171], v[120:123], v[72:75]
	v_exp_f32_e32 v64, v64
	v_mfma_f32_16x16x32_bf16 v[76:79], v[168:171], v[144:147], v[76:79]
	v_exp_f32_e32 v65, v65
	ds_read_b128 v[168:171], v202 offset:12288
	s_waitcnt lgkmcnt(3)
	v_mfma_f32_16x16x32_bf16 v[72:75], v[172:175], v[124:127], v[72:75]
	v_exp_f32_e32 v66, v66
	v_mfma_f32_16x16x32_bf16 v[76:79], v[172:175], v[148:151], v[76:79]
	v_exp_f32_e32 v67, v67
	ds_read_b128 v[172:175], v203 offset:12288
	s_waitcnt lgkmcnt(3)
	v_mfma_f32_16x16x32_bf16 v[72:75], v[176:179], v[128:131], v[72:75]
	v_exp_f32_e32 v68, v68
	v_mfma_f32_16x16x32_bf16 v[76:79], v[176:179], v[152:155], v[76:79]
	v_exp_f32_e32 v69, v69
	ds_read_b128 v[176:179], v202 offset:12416
	s_waitcnt lgkmcnt(3)
	v_mfma_f32_16x16x32_bf16 v[72:75], v[180:183], v[132:135], v[72:75]
	v_exp_f32_e32 v70, v70
	v_mfma_f32_16x16x32_bf16 v[76:79], v[180:183], v[156:159], v[76:79]
	v_exp_f32_e32 v71, v71
	ds_read_b128 v[180:183], v203 offset:12416
	s_waitcnt lgkmcnt(3)
	v_mfma_f32_16x16x32_bf16 v[80:83], v[168:171], v[112:115], v[160:163]
	v_mfma_f32_16x16x32_bf16 v[84:87], v[168:171], v[136:139], v[164:167]
	ds_read_b128 v[168:171], v202 offset:12544
	s_waitcnt lgkmcnt(3)
	v_mfma_f32_16x16x32_bf16 v[80:83], v[172:175], v[116:119], v[80:83]
	v_mfma_f32_16x16x32_bf16 v[84:87], v[172:175], v[140:143], v[84:87]
	ds_read_b128 v[172:175], v203 offset:12544
	s_waitcnt lgkmcnt(3)
	v_mfma_f32_16x16x32_bf16 v[80:83], v[176:179], v[120:123], v[80:83]
	v_exp_f32_e32 v72, v72
	v_mfma_f32_16x16x32_bf16 v[84:87], v[176:179], v[144:147], v[84:87]
	v_exp_f32_e32 v73, v73
	ds_read_b128 v[176:179], v202 offset:18432
	s_waitcnt lgkmcnt(3)
	v_mfma_f32_16x16x32_bf16 v[80:83], v[180:183], v[124:127], v[80:83]
	v_exp_f32_e32 v74, v74
	v_mfma_f32_16x16x32_bf16 v[84:87], v[180:183], v[148:151], v[84:87]
	v_exp_f32_e32 v75, v75
	ds_read_b128 v[180:183], v203 offset:18432
	s_waitcnt lgkmcnt(3)
	v_mfma_f32_16x16x32_bf16 v[80:83], v[168:171], v[128:131], v[80:83]
	v_exp_f32_e32 v76, v76
	v_mfma_f32_16x16x32_bf16 v[84:87], v[168:171], v[152:155], v[84:87]
	v_exp_f32_e32 v77, v77
	ds_read_b128 v[168:171], v202 offset:18560
	s_waitcnt lgkmcnt(3)
	v_mfma_f32_16x16x32_bf16 v[80:83], v[172:175], v[132:135], v[80:83]
	v_exp_f32_e32 v78, v78
	v_mfma_f32_16x16x32_bf16 v[84:87], v[172:175], v[156:159], v[84:87]
	v_exp_f32_e32 v79, v79
	ds_read_b128 v[172:175], v203 offset:18560
	s_waitcnt lgkmcnt(3)
	v_mfma_f32_16x16x32_bf16 v[88:91], v[176:179], v[112:115], v[160:163]
	v_mfma_f32_16x16x32_bf16 v[92:95], v[176:179], v[136:139], v[164:167]
	ds_read_b128 v[176:179], v202 offset:18688
	s_waitcnt lgkmcnt(3)
	v_mfma_f32_16x16x32_bf16 v[88:91], v[180:183], v[116:119], v[88:91]
	v_mfma_f32_16x16x32_bf16 v[92:95], v[180:183], v[140:143], v[92:95]
	ds_read_b128 v[180:183], v203 offset:18688
	s_waitcnt lgkmcnt(3)
	v_mfma_f32_16x16x32_bf16 v[88:91], v[168:171], v[120:123], v[88:91]
	v_exp_f32_e32 v80, v80
	v_mfma_f32_16x16x32_bf16 v[92:95], v[168:171], v[144:147], v[92:95]
	v_exp_f32_e32 v81, v81
	s_waitcnt lgkmcnt(2)
	v_mfma_f32_16x16x32_bf16 v[88:91], v[172:175], v[124:127], v[88:91]
	v_exp_f32_e32 v82, v82
	v_mfma_f32_16x16x32_bf16 v[92:95], v[172:175], v[148:151], v[92:95]
	v_exp_f32_e32 v83, v83
	s_waitcnt lgkmcnt(1)
	v_mfma_f32_16x16x32_bf16 v[88:91], v[176:179], v[128:131], v[88:91]
	v_exp_f32_e32 v84, v84
	v_mfma_f32_16x16x32_bf16 v[92:95], v[176:179], v[152:155], v[92:95]
	v_exp_f32_e32 v85, v85
	s_waitcnt lgkmcnt(0)
	v_mfma_f32_16x16x32_bf16 v[88:91], v[180:183], v[132:135], v[88:91]
	v_exp_f32_e32 v86, v86
	v_mfma_f32_16x16x32_bf16 v[92:95], v[180:183], v[156:159], v[92:95]
	v_exp_f32_e32 v87, v87
	ds_read_b64_tr_b16 v[184:185], v206 offset:49152
	ds_read_b64_tr_b16 v[186:187], v207 offset:49408
	ds_read_b64_tr_b16 v[188:189], v208 offset:49152
	ds_read_b64_tr_b16 v[190:191], v209 offset:49408
	ds_read_b64_tr_b16 v[192:193], v206 offset:49664
	ds_read_b64_tr_b16 v[194:195], v207 offset:49920
	s_nop 0
	s_nop 0
	s_nop 0
	v_exp_f32_e32 v88, v88
	v_exp_f32_e32 v89, v89
	v_exp_f32_e32 v90, v90
	v_exp_f32_e32 v91, v91
	v_exp_f32_e32 v92, v92
	v_exp_f32_e32 v93, v93
	v_exp_f32_e32 v94, v94
	v_exp_f32_e32 v95, v95
	v_add_f32_e32 v200, v200, v64
	v_add_f32_e32 v200, v200, v65
	v_add_f32_e32 v200, v200, v66
	v_add_f32_e32 v200, v200, v67
	v_add_f32_e32 v200, v200, v72
	v_add_f32_e32 v200, v200, v73
	v_add_f32_e32 v200, v200, v74
	v_add_f32_e32 v200, v200, v75
	v_add_f32_e32 v200, v200, v80
	v_add_f32_e32 v200, v200, v81
	v_add_f32_e32 v200, v200, v82
	v_add_f32_e32 v200, v200, v83
	v_add_f32_e32 v200, v200, v88
	v_add_f32_e32 v200, v200, v89
	v_add_f32_e32 v200, v200, v90
	v_add_f32_e32 v200, v200, v91
	v_add_f32_e32 v201, v201, v68
	v_add_f32_e32 v201, v201, v69
	v_add_f32_e32 v201, v201, v70
	v_add_f32_e32 v201, v201, v71
	v_add_f32_e32 v201, v201, v76
	v_add_f32_e32 v201, v201, v77
	v_add_f32_e32 v201, v201, v78
	v_add_f32_e32 v201, v201, v79
	v_add_f32_e32 v201, v201, v84
	v_add_f32_e32 v201, v201, v85
	v_add_f32_e32 v201, v201, v86
	v_add_f32_e32 v201, v201, v87
	v_add_f32_e32 v201, v201, v92
	v_add_f32_e32 v201, v201, v93
	v_add_f32_e32 v201, v201, v94
	v_add_f32_e32 v201, v201, v95
	v_cvt_pk_bf16_f32 v96, v64, v65
	v_cvt_pk_bf16_f32 v97, v66, v67
	v_cvt_pk_bf16_f32 v98, v72, v73
	v_cvt_pk_bf16_f32 v99, v74, v75
	v_cvt_pk_bf16_f32 v100, v80, v81
	v_cvt_pk_bf16_f32 v101, v82, v83
	v_cvt_pk_bf16_f32 v102, v88, v89
	v_cvt_pk_bf16_f32 v103, v90, v91
	v_cvt_pk_bf16_f32 v104, v68, v69
	v_cvt_pk_bf16_f32 v105, v70, v71
	v_cvt_pk_bf16_f32 v106, v76, v77
	v_cvt_pk_bf16_f32 v107, v78, v79
	v_cvt_pk_bf16_f32 v108, v84, v85
	v_cvt_pk_bf16_f32 v109, v86, v87
	v_cvt_pk_bf16_f32 v110, v92, v93
	v_cvt_pk_bf16_f32 v111, v94, v95
	ds_read_b64_tr_b16 v[196:197], v208 offset:49664
	ds_read_b64_tr_b16 v[198:199], v209 offset:49920
	s_waitcnt lgkmcnt(6)
	v_mfma_f32_16x16x32_bf16 v[0:3], v[96:99], v[184:187], v[0:3]
	v_mfma_f32_16x16x32_bf16 v[32:35], v[104:107], v[184:187], v[32:35]
	ds_read_b64_tr_b16 v[184:185], v206 offset:50176
	ds_read_b64_tr_b16 v[186:187], v207 offset:50432
	s_waitcnt lgkmcnt(6)
	v_mfma_f32_16x16x32_bf16 v[4:7], v[96:99], v[188:191], v[4:7]
	v_mfma_f32_16x16x32_bf16 v[36:39], v[104:107], v[188:191], v[36:39]
	ds_read_b64_tr_b16 v[188:189], v208 offset:50176
	ds_read_b64_tr_b16 v[190:191], v209 offset:50432
	s_waitcnt lgkmcnt(6)
	v_mfma_f32_16x16x32_bf16 v[8:11], v[96:99], v[192:195], v[8:11]
	v_mfma_f32_16x16x32_bf16 v[40:43], v[104:107], v[192:195], v[40:43]
	ds_read_b64_tr_b16 v[192:193], v206 offset:50688
	ds_read_b64_tr_b16 v[194:195], v207 offset:50944
	s_waitcnt lgkmcnt(6)
	v_mfma_f32_16x16x32_bf16 v[12:15], v[96:99], v[196:199], v[12:15]
	v_mfma_f32_16x16x32_bf16 v[44:47], v[104:107], v[196:199], v[44:47]
	ds_read_b64_tr_b16 v[196:197], v208 offset:50688
	ds_read_b64_tr_b16 v[198:199], v209 offset:50944
	s_waitcnt lgkmcnt(6)
	v_mfma_f32_16x16x32_bf16 v[16:19], v[96:99], v[184:187], v[16:19]
	v_mfma_f32_16x16x32_bf16 v[48:51], v[104:107], v[184:187], v[48:51]
	ds_read_b64_tr_b16 v[184:185], v206 offset:57344
	ds_read_b64_tr_b16 v[186:187], v207 offset:57600
	s_waitcnt lgkmcnt(6)
	v_mfma_f32_16x16x32_bf16 v[20:23], v[96:99], v[188:191], v[20:23]
	v_mfma_f32_16x16x32_bf16 v[52:55], v[104:107], v[188:191], v[52:55]
	ds_read_b64_tr_b16 v[188:189], v208 offset:57344
	ds_read_b64_tr_b16 v[190:191], v209 offset:57600
	s_waitcnt lgkmcnt(6)
	v_mfma_f32_16x16x32_bf16 v[24:27], v[96:99], v[192:195], v[24:27]
	v_mfma_f32_16x16x32_bf16 v[56:59], v[104:107], v[192:195], v[56:59]
	ds_read_b64_tr_b16 v[192:193], v206 offset:57856
	ds_read_b64_tr_b16 v[194:195], v207 offset:58112
	s_waitcnt lgkmcnt(6)
	v_mfma_f32_16x16x32_bf16 v[28:31], v[96:99], v[196:199], v[28:31]
	v_mfma_f32_16x16x32_bf16 v[60:63], v[104:107], v[196:199], v[60:63]
	ds_read_b64_tr_b16 v[196:197], v208 offset:57856
	ds_read_b64_tr_b16 v[198:199], v209 offset:58112
	s_waitcnt lgkmcnt(6)
	v_mfma_f32_16x16x32_bf16 v[0:3], v[100:103], v[184:187], v[0:3]
	v_mfma_f32_16x16x32_bf16 v[32:35], v[108:111], v[184:187], v[32:35]
	ds_read_b64_tr_b16 v[184:185], v206 offset:58368
	ds_read_b64_tr_b16 v[186:187], v207 offset:58624
	s_waitcnt lgkmcnt(6)
	v_mfma_f32_16x16x32_bf16 v[4:7], v[100:103], v[188:191], v[4:7]
	v_mfma_f32_16x16x32_bf16 v[36:39], v[108:111], v[188:191], v[36:39]
	ds_read_b64_tr_b16 v[188:189], v208 offset:58368
	ds_read_b64_tr_b16 v[190:191], v209 offset:58624
	s_waitcnt lgkmcnt(6)
	v_mfma_f32_16x16x32_bf16 v[8:11], v[100:103], v[192:195], v[8:11]
	v_mfma_f32_16x16x32_bf16 v[40:43], v[108:111], v[192:195], v[40:43]
	ds_read_b64_tr_b16 v[192:193], v206 offset:58880
	ds_read_b64_tr_b16 v[194:195], v207 offset:59136
	s_waitcnt lgkmcnt(6)
	v_mfma_f32_16x16x32_bf16 v[12:15], v[100:103], v[196:199], v[12:15]
	v_mfma_f32_16x16x32_bf16 v[44:47], v[108:111], v[196:199], v[44:47]
	ds_read_b64_tr_b16 v[196:197], v208 offset:58880
	ds_read_b64_tr_b16 v[198:199], v209 offset:59136
	s_waitcnt lgkmcnt(6)
	v_mfma_f32_16x16x32_bf16 v[16:19], v[100:103], v[184:187], v[16:19]
	v_mfma_f32_16x16x32_bf16 v[48:51], v[108:111], v[184:187], v[48:51]
	s_waitcnt lgkmcnt(4)
	v_mfma_f32_16x16x32_bf16 v[20:23], v[100:103], v[188:191], v[20:23]
	v_mfma_f32_16x16x32_bf16 v[52:55], v[108:111], v[188:191], v[52:55]
	s_waitcnt lgkmcnt(2)
	v_mfma_f32_16x16x32_bf16 v[24:27], v[100:103], v[192:195], v[24:27]
	v_mfma_f32_16x16x32_bf16 v[56:59], v[108:111], v[192:195], v[56:59]
	s_waitcnt lgkmcnt(0)
	v_mfma_f32_16x16x32_bf16 v[28:31], v[100:103], v[196:199], v[28:31]
	v_mfma_f32_16x16x32_bf16 v[60:63], v[108:111], v[196:199], v[60:63]
	s_waitcnt vmcnt(0) lgkmcnt(0)
	s_barrier
	s_add_i32 s14, s14, 2
	s_cmpk_ge_u32 s14, 256
	s_cbranch_scc1 .Lmla_lastodd
	s_mov_b32 m0, s46
	s_nop 0
	buffer_load_dwordx4 v210, s[4:7], s12 offen lds
	s_mov_b32 m0, s47
	s_nop 0
	buffer_load_dwordx4 v211, s[4:7], s12 offen lds
	s_mov_b32 m0, s48
	s_nop 0
	buffer_load_dwordx4 v212, s[4:7], s12 offen lds
	s_mov_b32 m0, s52
	s_nop 0
	buffer_load_dwordx4 v213, s[8:11], s13 offen lds
	s_mov_b32 m0, s53
	s_nop 0
	buffer_load_dwordx4 v214, s[8:11], s13 offen lds
	s_add_i32 s12, s12, 0x30000
	s_add_i32 s13, s13, 0x20000
.Lmla_lastodd:
	ds_read_b128 v[168:171], v202 offset:24576
	ds_read_b128 v[172:175], v203 offset:24576
	ds_read_b128 v[176:179], v202 offset:24704
	ds_read_b128 v[180:183], v203 offset:24704
	s_waitcnt lgkmcnt(3)
	v_mfma_f32_16x16x32_bf16 v[64:67], v[168:171], v[112:115], v[160:163]
	v_mfma_f32_16x16x32_bf16 v[68:71], v[168:171], v[136:139], v[164:167]
	ds_read_b128 v[168:171], v202 offset:24832
	s_waitcnt lgkmcnt(3)
	v_mfma_f32_16x16x32_bf16 v[64:67], v[172:175], v[116:119], v[64:67]
	v_mfma_f32_16x16x32_bf16 v[68:71], v[172:175], v[140:143], v[68:71]
	ds_read_b128 v[172:175], v203 offset:24832
	s_waitcnt lgkmcnt(3)
	v_mfma_f32_16x16x32_bf16 v[64:67], v[176:179], v[120:123], v[64:67]
	v_mfma_f32_16x16x32_bf16 v[68:71], v[176:179], v[144:147], v[68:71]
	ds_read_b128 v[176:179], v202 offset:30720
	s_waitcnt lgkmcnt(3)
	v_mfma_f32_16x16x32_bf16 v[64:67], v[180:183], v[124:127], v[64:67]
	v_mfma_f32_16x16x32_bf16 v[68:71], v[180:183], v[148:151], v[68:71]
	ds_read_b128 v[180:183], v203 offset:30720
	s_waitcnt lgkmcnt(3)
	v_mfma_f32_16x16x32_bf16 v[64:67], v[168:171], v[128:131], v[64:67]
	v_mfma_f32_16x16x32_bf16 v[68:71], v[168:171], v[152:155], v[68:71]
	ds_read_b128 v[168:171], v202 offset:30848
	s_waitcnt lgkmcnt(3)
	v_mfma_f32_16x16x32_bf16 v[64:67], v[172:175], v[132:135], v[64:67]
	v_mfma_f32_16x16x32_bf16 v[68:71], v[172:175], v[156:159], v[68:71]
	ds_read_b128 v[172:175], v203 offset:30848
	s_waitcnt lgkmcnt(3)
	v_mfma_f32_16x16x32_bf16 v[72:75], v[176:179], v[112:115], v[160:163]
	v_mfma_f32_16x16x32_bf16 v[76:79], v[176:179], v[136:139], v[164:167]
	ds_read_b128 v[176:179], v202 offset:30976
	s_waitcnt lgkmcnt(3)
	v_mfma_f32_16x16x32_bf16 v[72:75], v[180:183], v[116:119], v[72:75]
	v_mfma_f32_16x16x32_bf16 v[76:79], v[180:183], v[140:143], v[76:79]
	ds_read_b128 v[180:183], v203 offset:30976
	s_waitcnt lgkmcnt(3)
	v_mfma_f32_16x16x32_bf16 v[72:75], v[168:171], v[120:123], v[72:75]
	v_exp_f32_e32 v64, v64
	v_mfma_f32_16x16x32_bf16 v[76:79], v[168:171], v[144:147], v[76:79]
	v_exp_f32_e32 v65, v65
	ds_read_b128 v[168:171], v202 offset:36864
	s_waitcnt lgkmcnt(3)
	v_mfma_f32_16x16x32_bf16 v[72:75], v[172:175], v[124:127], v[72:75]
	v_exp_f32_e32 v66, v66
	v_mfma_f32_16x16x32_bf16 v[76:79], v[172:175], v[148:151], v[76:79]
	v_exp_f32_e32 v67, v67
	ds_read_b128 v[172:175], v203 offset:36864
	s_waitcnt lgkmcnt(3)
	v_mfma_f32_16x16x32_bf16 v[72:75], v[176:179], v[128:131], v[72:75]
	v_exp_f32_e32 v68, v68
	v_mfma_f32_16x16x32_bf16 v[76:79], v[176:179], v[152:155], v[76:79]
	v_exp_f32_e32 v69, v69
	ds_read_b128 v[176:179], v202 offset:36992
	s_waitcnt lgkmcnt(3)
	v_mfma_f32_16x16x32_bf16 v[72:75], v[180:183], v[132:135], v[72:75]
	v_exp_f32_e32 v70, v70
	v_mfma_f32_16x16x32_bf16 v[76:79], v[180:183], v[156:159], v[76:79]
	v_exp_f32_e32 v71, v71
	ds_read_b128 v[180:183], v203 offset:36992
	s_waitcnt lgkmcnt(3)
	v_mfma_f32_16x16x32_bf16 v[80:83], v[168:171], v[112:115], v[160:163]
	v_mfma_f32_16x16x32_bf16 v[84:87], v[168:171], v[136:139], v[164:167]
	ds_read_b128 v[168:171], v202 offset:37120
	s_waitcnt lgkmcnt(3)
	v_mfma_f32_16x16x32_bf16 v[80:83], v[172:175], v[116:119], v[80:83]
	v_mfma_f32_16x16x32_bf16 v[84:87], v[172:175], v[140:143], v[84:87]
	ds_read_b128 v[172:175], v203 offset:37120
	s_waitcnt lgkmcnt(3)
	v_mfma_f32_16x16x32_bf16 v[80:83], v[176:179], v[120:123], v[80:83]
	v_exp_f32_e32 v72, v72
	v_mfma_f32_16x16x32_bf16 v[84:87], v[176:179], v[144:147], v[84:87]
	v_exp_f32_e32 v73, v73
	ds_read_b128 v[176:179], v202 offset:43008
	s_waitcnt lgkmcnt(3)
	v_mfma_f32_16x16x32_bf16 v[80:83], v[180:183], v[124:127], v[80:83]
	v_exp_f32_e32 v74, v74
	v_mfma_f32_16x16x32_bf16 v[84:87], v[180:183], v[148:151], v[84:87]
	v_exp_f32_e32 v75, v75
	ds_read_b128 v[180:183], v203 offset:43008
	s_waitcnt lgkmcnt(3)
	v_mfma_f32_16x16x32_bf16 v[80:83], v[168:171], v[128:131], v[80:83]
	v_exp_f32_e32 v76, v76
	v_mfma_f32_16x16x32_bf16 v[84:87], v[168:171], v[152:155], v[84:87]
	v_exp_f32_e32 v77, v77
	ds_read_b128 v[168:171], v202 offset:43136
	s_waitcnt lgkmcnt(3)
	v_mfma_f32_16x16x32_bf16 v[80:83], v[172:175], v[132:135], v[80:83]
	v_exp_f32_e32 v78, v78
	v_mfma_f32_16x16x32_bf16 v[84:87], v[172:175], v[156:159], v[84:87]
	v_exp_f32_e32 v79, v79
	ds_read_b128 v[172:175], v203 offset:43136
	s_waitcnt lgkmcnt(3)
	v_mfma_f32_16x16x32_bf16 v[88:91], v[176:179], v[112:115], v[160:163]
	v_mfma_f32_16x16x32_bf16 v[92:95], v[176:179], v[136:139], v[164:167]
	ds_read_b128 v[176:179], v202 offset:43264
	s_waitcnt lgkmcnt(3)
	v_mfma_f32_16x16x32_bf16 v[88:91], v[180:183], v[116:119], v[88:91]
	v_mfma_f32_16x16x32_bf16 v[92:95], v[180:183], v[140:143], v[92:95]
	ds_read_b128 v[180:183], v203 offset:43264
	s_waitcnt lgkmcnt(3)
	v_mfma_f32_16x16x32_bf16 v[88:91], v[168:171], v[120:123], v[88:91]
	v_exp_f32_e32 v80, v80
	v_mfma_f32_16x16x32_bf16 v[92:95], v[168:171], v[144:147], v[92:95]
	v_exp_f32_e32 v81, v81
	s_waitcnt lgkmcnt(2)
	v_mfma_f32_16x16x32_bf16 v[88:91], v[172:175], v[124:127], v[88:91]
	v_exp_f32_e32 v82, v82
	v_mfma_f32_16x16x32_bf16 v[92:95], v[172:175], v[148:151], v[92:95]
	v_exp_f32_e32 v83, v83
	s_waitcnt lgkmcnt(1)
	v_mfma_f32_16x16x32_bf16 v[88:91], v[176:179], v[128:131], v[88:91]
	v_exp_f32_e32 v84, v84
	v_mfma_f32_16x16x32_bf16 v[92:95], v[176:179], v[152:155], v[92:95]
	v_exp_f32_e32 v85, v85
	s_waitcnt lgkmcnt(0)
	v_mfma_f32_16x16x32_bf16 v[88:91], v[180:183], v[132:135], v[88:91]
	v_exp_f32_e32 v86, v86
	v_mfma_f32_16x16x32_bf16 v[92:95], v[180:183], v[156:159], v[92:95]
	v_exp_f32_e32 v87, v87
	ds_read_b64_tr_b16 v[184:185], v250 offset:49152
	ds_read_b64_tr_b16 v[186:187], v251 offset:49408
	ds_read_b64_tr_b16 v[188:189], v252 offset:49152
	ds_read_b64_tr_b16 v[190:191], v253 offset:49408
	ds_read_b64_tr_b16 v[192:193], v250 offset:49664
	ds_read_b64_tr_b16 v[194:195], v251 offset:49920
	s_nop 0
	s_nop 0
	s_nop 0
	v_exp_f32_e32 v88, v88
	v_exp_f32_e32 v89, v89
	v_exp_f32_e32 v90, v90
	v_exp_f32_e32 v91, v91
	v_exp_f32_e32 v92, v92
	v_exp_f32_e32 v93, v93
	v_exp_f32_e32 v94, v94
	v_exp_f32_e32 v95, v95
	v_add_f32_e32 v200, v200, v64
	v_add_f32_e32 v200, v200, v65
	v_add_f32_e32 v200, v200, v66
	v_add_f32_e32 v200, v200, v67
	v_add_f32_e32 v200, v200, v72
	v_add_f32_e32 v200, v200, v73
	v_add_f32_e32 v200, v200, v74
	v_add_f32_e32 v200, v200, v75
	v_add_f32_e32 v200, v200, v80
	v_add_f32_e32 v200, v200, v81
	v_add_f32_e32 v200, v200, v82
	v_add_f32_e32 v200, v200, v83
	v_add_f32_e32 v200, v200, v88
	v_add_f32_e32 v200, v200, v89
	v_add_f32_e32 v200, v200, v90
	v_add_f32_e32 v200, v200, v91
	v_add_f32_e32 v201, v201, v68
	v_add_f32_e32 v201, v201, v69
	v_add_f32_e32 v201, v201, v70
	v_add_f32_e32 v201, v201, v71
	v_add_f32_e32 v201, v201, v76
	v_add_f32_e32 v201, v201, v77
	v_add_f32_e32 v201, v201, v78
	v_add_f32_e32 v201, v201, v79
	v_add_f32_e32 v201, v201, v84
	v_add_f32_e32 v201, v201, v85
	v_add_f32_e32 v201, v201, v86
	v_add_f32_e32 v201, v201, v87
	v_add_f32_e32 v201, v201, v92
	v_add_f32_e32 v201, v201, v93
	v_add_f32_e32 v201, v201, v94
	v_add_f32_e32 v201, v201, v95
	v_cvt_pk_bf16_f32 v96, v64, v65
	v_cvt_pk_bf16_f32 v97, v66, v67
	v_cvt_pk_bf16_f32 v98, v72, v73
	v_cvt_pk_bf16_f32 v99, v74, v75
	v_cvt_pk_bf16_f32 v100, v80, v81
	v_cvt_pk_bf16_f32 v101, v82, v83
	v_cvt_pk_bf16_f32 v102, v88, v89
	v_cvt_pk_bf16_f32 v103, v90, v91
	v_cvt_pk_bf16_f32 v104, v68, v69
	v_cvt_pk_bf16_f32 v105, v70, v71
	v_cvt_pk_bf16_f32 v106, v76, v77
	v_cvt_pk_bf16_f32 v107, v78, v79
	v_cvt_pk_bf16_f32 v108, v84, v85
	v_cvt_pk_bf16_f32 v109, v86, v87
	v_cvt_pk_bf16_f32 v110, v92, v93
	v_cvt_pk_bf16_f32 v111, v94, v95
	ds_read_b64_tr_b16 v[196:197], v252 offset:49664
	ds_read_b64_tr_b16 v[198:199], v253 offset:49920
	s_waitcnt lgkmcnt(6)
	v_mfma_f32_16x16x32_bf16 v[0:3], v[96:99], v[184:187], v[0:3]
	v_mfma_f32_16x16x32_bf16 v[32:35], v[104:107], v[184:187], v[32:35]
	ds_read_b64_tr_b16 v[184:185], v250 offset:50176
	ds_read_b64_tr_b16 v[186:187], v251 offset:50432
	s_waitcnt lgkmcnt(6)
	v_mfma_f32_16x16x32_bf16 v[4:7], v[96:99], v[188:191], v[4:7]
	v_mfma_f32_16x16x32_bf16 v[36:39], v[104:107], v[188:191], v[36:39]
	ds_read_b64_tr_b16 v[188:189], v252 offset:50176
	ds_read_b64_tr_b16 v[190:191], v253 offset:50432
	s_waitcnt lgkmcnt(6)
	v_mfma_f32_16x16x32_bf16 v[8:11], v[96:99], v[192:195], v[8:11]
	v_mfma_f32_16x16x32_bf16 v[40:43], v[104:107], v[192:195], v[40:43]
	ds_read_b64_tr_b16 v[192:193], v250 offset:50688
	ds_read_b64_tr_b16 v[194:195], v251 offset:50944
	s_waitcnt lgkmcnt(6)
	v_mfma_f32_16x16x32_bf16 v[12:15], v[96:99], v[196:199], v[12:15]
	v_mfma_f32_16x16x32_bf16 v[44:47], v[104:107], v[196:199], v[44:47]
	ds_read_b64_tr_b16 v[196:197], v252 offset:50688
	ds_read_b64_tr_b16 v[198:199], v253 offset:50944
	s_waitcnt lgkmcnt(6)
	v_mfma_f32_16x16x32_bf16 v[16:19], v[96:99], v[184:187], v[16:19]
	v_mfma_f32_16x16x32_bf16 v[48:51], v[104:107], v[184:187], v[48:51]
	ds_read_b64_tr_b16 v[184:185], v250 offset:57344
	ds_read_b64_tr_b16 v[186:187], v251 offset:57600
	s_waitcnt lgkmcnt(6)
	v_mfma_f32_16x16x32_bf16 v[20:23], v[96:99], v[188:191], v[20:23]
	v_mfma_f32_16x16x32_bf16 v[52:55], v[104:107], v[188:191], v[52:55]
	ds_read_b64_tr_b16 v[188:189], v252 offset:57344
	ds_read_b64_tr_b16 v[190:191], v253 offset:57600
	s_waitcnt lgkmcnt(6)
	v_mfma_f32_16x16x32_bf16 v[24:27], v[96:99], v[192:195], v[24:27]
	v_mfma_f32_16x16x32_bf16 v[56:59], v[104:107], v[192:195], v[56:59]
	ds_read_b64_tr_b16 v[192:193], v250 offset:57856
	ds_read_b64_tr_b16 v[194:195], v251 offset:58112
	s_waitcnt lgkmcnt(6)
	v_mfma_f32_16x16x32_bf16 v[28:31], v[96:99], v[196:199], v[28:31]
	v_mfma_f32_16x16x32_bf16 v[60:63], v[104:107], v[196:199], v[60:63]
	ds_read_b64_tr_b16 v[196:197], v252 offset:57856
	ds_read_b64_tr_b16 v[198:199], v253 offset:58112
	s_waitcnt lgkmcnt(6)
	v_mfma_f32_16x16x32_bf16 v[0:3], v[100:103], v[184:187], v[0:3]
	v_mfma_f32_16x16x32_bf16 v[32:35], v[108:111], v[184:187], v[32:35]
	ds_read_b64_tr_b16 v[184:185], v250 offset:58368
	ds_read_b64_tr_b16 v[186:187], v251 offset:58624
	s_waitcnt lgkmcnt(6)
	v_mfma_f32_16x16x32_bf16 v[4:7], v[100:103], v[188:191], v[4:7]
	v_mfma_f32_16x16x32_bf16 v[36:39], v[108:111], v[188:191], v[36:39]
	ds_read_b64_tr_b16 v[188:189], v252 offset:58368
	ds_read_b64_tr_b16 v[190:191], v253 offset:58624
	s_waitcnt lgkmcnt(6)
	v_mfma_f32_16x16x32_bf16 v[8:11], v[100:103], v[192:195], v[8:11]
	v_mfma_f32_16x16x32_bf16 v[40:43], v[108:111], v[192:195], v[40:43]
	ds_read_b64_tr_b16 v[192:193], v250 offset:58880
	ds_read_b64_tr_b16 v[194:195], v251 offset:59136
	s_waitcnt lgkmcnt(6)
	v_mfma_f32_16x16x32_bf16 v[12:15], v[100:103], v[196:199], v[12:15]
	v_mfma_f32_16x16x32_bf16 v[44:47], v[108:111], v[196:199], v[44:47]
	ds_read_b64_tr_b16 v[196:197], v252 offset:58880
	ds_read_b64_tr_b16 v[198:199], v253 offset:59136
	s_waitcnt lgkmcnt(6)
	v_mfma_f32_16x16x32_bf16 v[16:19], v[100:103], v[184:187], v[16:19]
	v_mfma_f32_16x16x32_bf16 v[48:51], v[108:111], v[184:187], v[48:51]
	s_waitcnt lgkmcnt(4)
	v_mfma_f32_16x16x32_bf16 v[20:23], v[100:103], v[188:191], v[20:23]
	v_mfma_f32_16x16x32_bf16 v[52:55], v[108:111], v[188:191], v[52:55]
	s_waitcnt lgkmcnt(2)
	v_mfma_f32_16x16x32_bf16 v[24:27], v[100:103], v[192:195], v[24:27]
	v_mfma_f32_16x16x32_bf16 v[56:59], v[108:111], v[192:195], v[56:59]
	s_waitcnt lgkmcnt(0)
	v_mfma_f32_16x16x32_bf16 v[28:31], v[100:103], v[196:199], v[28:31]
	v_mfma_f32_16x16x32_bf16 v[60:63], v[108:111], v[196:199], v[60:63]
	s_waitcnt vmcnt(0) lgkmcnt(0)
	s_barrier
	s_cmpk_lt_u32 s14, 256
	s_cbranch_scc1 .Lmla_tiles
	ds_write_b32 v245, v200 offset:0
	ds_write_b32 v245, v201 offset:256
	s_waitcnt lgkmcnt(0)
	ds_read_b128 v[218:221], v247 offset:0
	ds_read_b128 v[222:225], v247 offset:64
	ds_read_b128 v[226:229], v247 offset:128
	ds_read_b128 v[230:233], v247 offset:192
	s_waitcnt lgkmcnt(2)
	v_add_f32_e32 v218, v218, v222
	s_waitcnt lgkmcnt(0)
	v_add_f32_e32 v226, v226, v230
	v_add_f32_e32 v218, v218, v226
	v_rcp_f32_e32 v234, v218
	v_add_f32_e32 v219, v219, v223
	v_add_f32_e32 v227, v227, v231
	v_add_f32_e32 v219, v219, v227
	v_rcp_f32_e32 v235, v219
	v_add_f32_e32 v220, v220, v224
	v_add_f32_e32 v228, v228, v232
	v_add_f32_e32 v220, v220, v228
	v_rcp_f32_e32 v236, v220
	v_add_f32_e32 v221, v221, v225
	v_add_f32_e32 v229, v229, v233
	v_add_f32_e32 v221, v221, v229
	v_rcp_f32_e32 v237, v221
	ds_read_b128 v[218:221], v247 offset:256
	ds_read_b128 v[222:225], v247 offset:320
	ds_read_b128 v[226:229], v247 offset:384
	ds_read_b128 v[230:233], v247 offset:448
	s_waitcnt lgkmcnt(2)
	v_add_f32_e32 v218, v218, v222
	s_waitcnt lgkmcnt(0)
	v_add_f32_e32 v226, v226, v230
	v_add_f32_e32 v218, v218, v226
	v_rcp_f32_e32 v238, v218
	v_add_f32_e32 v219, v219, v223
	v_add_f32_e32 v227, v227, v231
	v_add_f32_e32 v219, v219, v227
	v_rcp_f32_e32 v239, v219
	v_add_f32_e32 v220, v220, v224
	v_add_f32_e32 v228, v228, v232
	v_add_f32_e32 v220, v220, v228
	v_rcp_f32_e32 v240, v220
	v_add_f32_e32 v221, v221, v225
	v_add_f32_e32 v229, v229, v233
	v_add_f32_e32 v221, v221, v229
	v_rcp_f32_e32 v241, v221
	s_nop 0
	v_add_u32_e32 v242, 0, v248
	v_mul_f32_e32 v0, v0, v234
	v_cvt_pk_bf16_f32 v243, v0, v249
	global_store_short v242, v243, s[18:19] offset:0
	v_mul_f32_e32 v4, v4, v234
	v_cvt_pk_bf16_f32 v244, v4, v249
	global_store_short v242, v244, s[18:19] offset:32
	v_mul_f32_e32 v8, v8, v234
	v_cvt_pk_bf16_f32 v243, v8, v249
	global_store_short v242, v243, s[18:19] offset:64
	v_mul_f32_e32 v12, v12, v234
	v_cvt_pk_bf16_f32 v244, v12, v249
	global_store_short v242, v244, s[18:19] offset:96
	v_mul_f32_e32 v16, v16, v234
	v_cvt_pk_bf16_f32 v243, v16, v249
	global_store_short v242, v243, s[18:19] offset:128
	v_mul_f32_e32 v20, v20, v234
	v_cvt_pk_bf16_f32 v244, v20, v249
	global_store_short v242, v244, s[18:19] offset:160
	v_mul_f32_e32 v24, v24, v234
	v_cvt_pk_bf16_f32 v243, v24, v249
	global_store_short v242, v243, s[18:19] offset:192
	v_mul_f32_e32 v28, v28, v234
	v_cvt_pk_bf16_f32 v244, v28, v249
	global_store_short v242, v244, s[18:19] offset:224
	v_add_u32_e32 v242, 4096, v248
	v_mul_f32_e32 v1, v1, v235
	v_cvt_pk_bf16_f32 v243, v1, v249
	global_store_short v242, v243, s[18:19] offset:0
	v_mul_f32_e32 v5, v5, v235
	v_cvt_pk_bf16_f32 v244, v5, v249
	global_store_short v242, v244, s[18:19] offset:32
	v_mul_f32_e32 v9, v9, v235
	v_cvt_pk_bf16_f32 v243, v9, v249
	global_store_short v242, v243, s[18:19] offset:64
	v_mul_f32_e32 v13, v13, v235
	v_cvt_pk_bf16_f32 v244, v13, v249
	global_store_short v242, v244, s[18:19] offset:96
	v_mul_f32_e32 v17, v17, v235
	v_cvt_pk_bf16_f32 v243, v17, v249
	global_store_short v242, v243, s[18:19] offset:128
	v_mul_f32_e32 v21, v21, v235
	v_cvt_pk_bf16_f32 v244, v21, v249
	global_store_short v242, v244, s[18:19] offset:160
	v_mul_f32_e32 v25, v25, v235
	v_cvt_pk_bf16_f32 v243, v25, v249
	global_store_short v242, v243, s[18:19] offset:192
	v_mul_f32_e32 v29, v29, v235
	v_cvt_pk_bf16_f32 v244, v29, v249
	global_store_short v242, v244, s[18:19] offset:224
	v_add_u32_e32 v242, 8192, v248
	v_mul_f32_e32 v2, v2, v236
	v_cvt_pk_bf16_f32 v243, v2, v249
	global_store_short v242, v243, s[18:19] offset:0
	v_mul_f32_e32 v6, v6, v236
	v_cvt_pk_bf16_f32 v244, v6, v249
	global_store_short v242, v244, s[18:19] offset:32
	v_mul_f32_e32 v10, v10, v236
	v_cvt_pk_bf16_f32 v243, v10, v249
	global_store_short v242, v243, s[18:19] offset:64
	v_mul_f32_e32 v14, v14, v236
	v_cvt_pk_bf16_f32 v244, v14, v249
	global_store_short v242, v244, s[18:19] offset:96
	v_mul_f32_e32 v18, v18, v236
	v_cvt_pk_bf16_f32 v243, v18, v249
	global_store_short v242, v243, s[18:19] offset:128
	v_mul_f32_e32 v22, v22, v236
	v_cvt_pk_bf16_f32 v244, v22, v249
	global_store_short v242, v244, s[18:19] offset:160
	v_mul_f32_e32 v26, v26, v236
	v_cvt_pk_bf16_f32 v243, v26, v249
	global_store_short v242, v243, s[18:19] offset:192
	v_mul_f32_e32 v30, v30, v236
	v_cvt_pk_bf16_f32 v244, v30, v249
	global_store_short v242, v244, s[18:19] offset:224
	v_add_u32_e32 v242, 12288, v248
	v_mul_f32_e32 v3, v3, v237
	v_cvt_pk_bf16_f32 v243, v3, v249
	global_store_short v242, v243, s[18:19] offset:0
	v_mul_f32_e32 v7, v7, v237
	v_cvt_pk_bf16_f32 v244, v7, v249
	global_store_short v242, v244, s[18:19] offset:32
	v_mul_f32_e32 v11, v11, v237
	v_cvt_pk_bf16_f32 v243, v11, v249
	global_store_short v242, v243, s[18:19] offset:64
	v_mul_f32_e32 v15, v15, v237
	v_cvt_pk_bf16_f32 v244, v15, v249
	global_store_short v242, v244, s[18:19] offset:96
	v_mul_f32_e32 v19, v19, v237
	v_cvt_pk_bf16_f32 v243, v19, v249
	global_store_short v242, v243, s[18:19] offset:128
	v_mul_f32_e32 v23, v23, v237
	v_cvt_pk_bf16_f32 v244, v23, v249
	global_store_short v242, v244, s[18:19] offset:160
	v_mul_f32_e32 v27, v27, v237
	v_cvt_pk_bf16_f32 v243, v27, v249
	global_store_short v242, v243, s[18:19] offset:192
	v_mul_f32_e32 v31, v31, v237
	v_cvt_pk_bf16_f32 v244, v31, v249
	global_store_short v242, v244, s[18:19] offset:224
	v_add_u32_e32 v242, 65536, v248
	v_mul_f32_e32 v32, v32, v238
	v_cvt_pk_bf16_f32 v243, v32, v249
	global_store_short v242, v243, s[18:19] offset:0
	v_mul_f32_e32 v36, v36, v238
	v_cvt_pk_bf16_f32 v244, v36, v249
	global_store_short v242, v244, s[18:19] offset:32
	v_mul_f32_e32 v40, v40, v238
	v_cvt_pk_bf16_f32 v243, v40, v249
	global_store_short v242, v243, s[18:19] offset:64
	v_mul_f32_e32 v44, v44, v238
	v_cvt_pk_bf16_f32 v244, v44, v249
	global_store_short v242, v244, s[18:19] offset:96
	v_mul_f32_e32 v48, v48, v238
	v_cvt_pk_bf16_f32 v243, v48, v249
	global_store_short v242, v243, s[18:19] offset:128
	v_mul_f32_e32 v52, v52, v238
	v_cvt_pk_bf16_f32 v244, v52, v249
	global_store_short v242, v244, s[18:19] offset:160
	v_mul_f32_e32 v56, v56, v238
	v_cvt_pk_bf16_f32 v243, v56, v249
	global_store_short v242, v243, s[18:19] offset:192
	v_mul_f32_e32 v60, v60, v238
	v_cvt_pk_bf16_f32 v244, v60, v249
	global_store_short v242, v244, s[18:19] offset:224
	v_add_u32_e32 v242, 69632, v248
	v_mul_f32_e32 v33, v33, v239
	v_cvt_pk_bf16_f32 v243, v33, v249
	global_store_short v242, v243, s[18:19] offset:0
	v_mul_f32_e32 v37, v37, v239
	v_cvt_pk_bf16_f32 v244, v37, v249
	global_store_short v242, v244, s[18:19] offset:32
	v_mul_f32_e32 v41, v41, v239
	v_cvt_pk_bf16_f32 v243, v41, v249
	global_store_short v242, v243, s[18:19] offset:64
	v_mul_f32_e32 v45, v45, v239
	v_cvt_pk_bf16_f32 v244, v45, v249
	global_store_short v242, v244, s[18:19] offset:96
	v_mul_f32_e32 v49, v49, v239
	v_cvt_pk_bf16_f32 v243, v49, v249
	global_store_short v242, v243, s[18:19] offset:128
	v_mul_f32_e32 v53, v53, v239
	v_cvt_pk_bf16_f32 v244, v53, v249
	global_store_short v242, v244, s[18:19] offset:160
	v_mul_f32_e32 v57, v57, v239
	v_cvt_pk_bf16_f32 v243, v57, v249
	global_store_short v242, v243, s[18:19] offset:192
	v_mul_f32_e32 v61, v61, v239
	v_cvt_pk_bf16_f32 v244, v61, v249
	global_store_short v242, v244, s[18:19] offset:224
	v_add_u32_e32 v242, 73728, v248
	v_mul_f32_e32 v34, v34, v240
	v_cvt_pk_bf16_f32 v243, v34, v249
	global_store_short v242, v243, s[18:19] offset:0
	v_mul_f32_e32 v38, v38, v240
	v_cvt_pk_bf16_f32 v244, v38, v249
	global_store_short v242, v244, s[18:19] offset:32
	v_mul_f32_e32 v42, v42, v240
	v_cvt_pk_bf16_f32 v243, v42, v249
	global_store_short v242, v243, s[18:19] offset:64
	v_mul_f32_e32 v46, v46, v240
	v_cvt_pk_bf16_f32 v244, v46, v249
	global_store_short v242, v244, s[18:19] offset:96
	v_mul_f32_e32 v50, v50, v240
	v_cvt_pk_bf16_f32 v243, v50, v249
	global_store_short v242, v243, s[18:19] offset:128
	v_mul_f32_e32 v54, v54, v240
	v_cvt_pk_bf16_f32 v244, v54, v249
	global_store_short v242, v244, s[18:19] offset:160
	v_mul_f32_e32 v58, v58, v240
	v_cvt_pk_bf16_f32 v243, v58, v249
	global_store_short v242, v243, s[18:19] offset:192
	v_mul_f32_e32 v62, v62, v240
	v_cvt_pk_bf16_f32 v244, v62, v249
	global_store_short v242, v244, s[18:19] offset:224
	v_add_u32_e32 v242, 77824, v248
	v_mul_f32_e32 v35, v35, v241
	v_cvt_pk_bf16_f32 v243, v35, v249
	global_store_short v242, v243, s[18:19] offset:0
	v_mul_f32_e32 v39, v39, v241
	v_cvt_pk_bf16_f32 v244, v39, v249
	global_store_short v242, v244, s[18:19] offset:32
	v_mul_f32_e32 v43, v43, v241
	v_cvt_pk_bf16_f32 v243, v43, v249
	global_store_short v242, v243, s[18:19] offset:64
	v_mul_f32_e32 v47, v47, v241
	v_cvt_pk_bf16_f32 v244, v47, v249
	global_store_short v242, v244, s[18:19] offset:96
	v_mul_f32_e32 v51, v51, v241
	v_cvt_pk_bf16_f32 v243, v51, v249
	global_store_short v242, v243, s[18:19] offset:128
	v_mul_f32_e32 v55, v55, v241
	v_cvt_pk_bf16_f32 v244, v55, v249
	global_store_short v242, v244, s[18:19] offset:160
	v_mul_f32_e32 v59, v59, v241
	v_cvt_pk_bf16_f32 v243, v59, v249
	global_store_short v242, v243, s[18:19] offset:192
	v_mul_f32_e32 v63, v63, v241
	v_cvt_pk_bf16_f32 v244, v63, v249
	global_store_short v242, v244, s[18:19] offset:224
	s_add_i32 s76, s76, s34
	s_cmpk_gt_i32 s76, 0x1ff
	s_cbranch_scc0 .Lmla_unit
.Lmla_done:
	s_branch .LBB0_491
